# v37 + invalidate-at-arrival also at the two prologue grid barriers (P0, P1)
# speedup vs baseline: 1.0024x; 1.0022x over previous
.LBB0_122:
	s_lshl_b32 s4, s3, 8
	s_add_u32 s4, s10, s4
	s_addc_u32 s5, s11, 0
	v_mov_b32_e32 v2, 0x1000
	v_mov_b32_e32 v4, 1
	global_atomic_add v4, v2, v4, s[4:5] offset:1024 sc0
	buffer_inv sc1
	v_cvt_f32_u32_e32 v2, v3
	v_sub_u32_e32 v5, 0, v3
	v_rcp_iflag_f32_e32 v2, v2
	s_nop 0
	v_mul_f32_e32 v2, 0x4f7ffffe, v2
	v_cvt_u32_f32_e32 v2, v2
	v_mul_lo_u32 v5, v5, v2
	v_mul_hi_u32 v5, v2, v5
	v_add_u32_e32 v2, v2, v5
	s_waitcnt vmcnt(1)
	v_mul_hi_u32 v2, v4, v2
	v_mul_lo_u32 v5, v2, v3
	v_sub_u32_e32 v5, v4, v5
	v_add_u32_e32 v6, 1, v2
	v_cmp_ge_u32_e32 vcc, v5, v3
	v_add_u32_e32 v4, 1, v4
	s_nop 0
	v_cndmask_b32_e32 v2, v2, v6, vcc
	v_sub_u32_e32 v6, v5, v3
	v_cndmask_b32_e32 v5, v5, v6, vcc
	v_add_u32_e32 v6, 1, v2
	v_cmp_ge_u32_e32 vcc, v5, v3
	s_nop 1
	v_cndmask_b32_e32 v2, v2, v6, vcc
	v_mul_lo_u32 v5, v3, v2
	v_add_u32_e32 v3, v5, v3
	v_cmp_ne_u32_e32 vcc, v4, v3
	s_and_saveexec_b64 s[6:7], vcc
	s_xor_b64 s[6:7], exec, s[6:7]
	s_cbranch_execz .LBB0_136
	s_waitcnt lgkmcnt(0)
	v_mov_b32_e32 v1, 0x2000
	global_load_dword v1, v1, s[4:5] offset:1024 sc1
	s_add_u32 s18, s4, 0x2400
	s_addc_u32 s19, s5, 0
	s_waitcnt vmcnt(0)
	v_cmp_eq_u32_e32 vcc, v1, v2
	s_and_saveexec_b64 s[8:9], vcc
	s_cbranch_execz .LBB0_135
	v_readlane_b32 s12, v252, 3
	v_readlane_b32 s14, v252, 5
	v_readlane_b32 s15, v252, 6
	s_add_u32 s16, s14, 0x4200
	s_addc_u32 s17, s15, 0
	s_mov_b32 s12, 1
	s_mov_b64 s[20:21], 0
	v_mov_b32_e32 v1, 0
	v_readlane_b32 s13, v252, 4
	s_branch .LBB0_126

.LBB0_135:
	s_or_b64 exec, exec, s[8:9]
	s_waitcnt vmcnt(0)
	s_nop 0
	s_waitcnt vmcnt(0)

.LBB0_153:
	s_or_b64 exec, exec, s[6:7]
	v_mov_b32_e32 v1, 0x2000
	v_mov_b32_e32 v2, 1
	s_waitcnt vmcnt(0)
	s_nop 0
	global_atomic_add v1, v2, s[4:5] offset:1024
	s_waitcnt vmcnt(0)
